# LN1 fused into the GEMM3 epilogue: y kept in f32 accumulators, per-tile row mean/M2 via LDS, 4-tile exchange through the workspace (write-through + drained counter), Chan combine; LN1 phase and its gr
# speedup vs baseline: 1.0134x; 1.0002x over previous
.LBB0_820:
	s_mov_b32 s23, s37
	s_ashr_i32 s1, s91, 2
	s_and_b32 s21, s1, 0xffffffc0
	s_lshl_b32 s1, s31, 8
	s_add_i32 s21, s21, s1
	v_and_b32_e32 v0, 15, v230
	v_add_u32_e32 v142, s21, v0
	s_lshr_b32 s0, s91, 1
	s_and_b32 s0, s0, 0x60
	s_lshl_b32 s1, s37, 8
	s_or_b32 s0, s1, s0
	v_lshrrev_b32_e32 v0, 1, v230
	v_and_b32_e32 v0, -8, v0
	v_add_u32_e32 v143, s0, v0
	v_lshlrev_b32_e32 v144, 12, v142
	v_lshl_add_u32 v144, v143, 2, v144
	v_lshlrev_b32_e32 v145, 11, v142
	v_lshl_add_u32 v145, v143, 1, v145
	v_lshlrev_b32_e32 v146, 2, v143
	s_mov_b32 s30, 0
	s_mov_b32 s31, s71
	s_xor_b64 s[30:31], s[30:31], s[12:13]
	s_mov_b32 s28, 0
	s_mov_b32 s29, s71
	s_xor_b64 s[28:29], s[28:29], s[14:15]
	s_sub_u32 s28, s28, 0x1000000
	s_subb_u32 s29, s29, 0
	s_cmp_lt_u32 s21, 0x1000
	s_cselect_b32 s28, s30, s28
	s_cselect_b32 s29, s31, s29
	s_mov_b32 s0, 0
	s_mov_b32 s1, s71
	s_xor_b64 s[0:1], s[0:1], s[62:63]
	s_add_u32 s8, s0, s18
	s_addc_u32 s9, s1, s19
	s_add_u32 s34, s8, 0x4a02000
	s_addc_u32 s35, s9, 0
	s_add_i32 s1, s21, 0xfffff000
	s_lshr_b32 s1, s1, 10
	s_mulk_i32 s1, 0x1800
	s_add_i32 s52, s1, 0x1800
	s_cmp_lt_u32 s21, 0x1000
	s_cselect_b32 s52, 0, s52
	s_lshl_b32 s52, s52, 2
	s_add_u32 s34, s34, s52
	s_addc_u32 s35, s35, 0
	global_load_dwordx4 v[152:155], v146, s[34:35]
	global_load_dwordx4 v[156:159], v146, s[34:35] offset:16
	global_load_dwordx4 v[160:163], v146, s[34:35] offset:512
	global_load_dwordx4 v[164:167], v146, s[34:35] offset:528
	global_load_dwordx4 v[168:171], v144, s[28:29]
	global_load_dwordx4 v[172:175], v144, s[28:29] offset:16
	global_load_dwordx4 v[176:179], v144, s[28:29] offset:512
	global_load_dwordx4 v[180:183], v144, s[28:29] offset:528
	v_add_u32_e32 v147, 0x10000, v144
	global_load_dwordx4 v[184:187], v147, s[28:29]
	global_load_dwordx4 v[188:191], v147, s[28:29] offset:16
	global_load_dwordx4 v[192:195], v147, s[28:29] offset:512
	global_load_dwordx4 v[202:205], v147, s[28:29] offset:528
	v_add_u32_e32 v147, 0x20000, v144
	global_load_dwordx4 v[206:209], v147, s[28:29]
	global_load_dwordx4 v[210:213], v147, s[28:29] offset:16
	global_load_dwordx4 v[214:217], v147, s[28:29] offset:512
	global_load_dwordx4 v[218:221], v147, s[28:29] offset:528
	s_mov_b32 s0, 0x3fb504f3
	s_waitcnt vmcnt(8)
	v_pk_mul_f32 v[128:129], v[128:129], v[154:155]
	v_pk_mul_f32 v[126:127], v[126:127], v[152:153]
	v_pk_fma_f32 v[128:129], v[170:171], s[0:1], v[128:129] op_sel_hi:[1,0,1]
	v_pk_fma_f32 v[126:127], v[168:169], s[0:1], v[126:127] op_sel_hi:[1,0,1]
	v_pk_mul_f32 v[124:125], v[124:125], v[158:159]
	v_pk_mul_f32 v[122:123], v[122:123], v[156:157]
	v_pk_fma_f32 v[124:125], v[174:175], s[0:1], v[124:125] op_sel_hi:[1,0,1]
	v_pk_fma_f32 v[122:123], v[172:173], s[0:1], v[122:123] op_sel_hi:[1,0,1]
	v_pk_mul_f32 v[120:121], v[120:121], v[162:163]
	v_pk_mul_f32 v[118:119], v[118:119], v[160:161]
	v_pk_fma_f32 v[120:121], v[178:179], s[0:1], v[120:121] op_sel_hi:[1,0,1]
	v_pk_fma_f32 v[118:119], v[176:177], s[0:1], v[118:119] op_sel_hi:[1,0,1]
	v_pk_mul_f32 v[116:117], v[116:117], v[166:167]
	v_pk_mul_f32 v[114:115], v[114:115], v[164:165]
	v_pk_fma_f32 v[116:117], v[182:183], s[0:1], v[116:117] op_sel_hi:[1,0,1]
	v_pk_fma_f32 v[114:115], v[180:181], s[0:1], v[114:115] op_sel_hi:[1,0,1]
	v_add_u32_e32 v147, 0x30000, v144
	global_load_dwordx4 v[168:171], v147, s[28:29]
	global_load_dwordx4 v[172:175], v147, s[28:29] offset:16
	global_load_dwordx4 v[176:179], v147, s[28:29] offset:512
	global_load_dwordx4 v[180:183], v147, s[28:29] offset:528
	s_waitcnt vmcnt(8)
	v_pk_mul_f32 v[112:113], v[112:113], v[154:155]
	v_pk_mul_f32 v[110:111], v[110:111], v[152:153]
	v_pk_fma_f32 v[112:113], v[186:187], s[0:1], v[112:113] op_sel_hi:[1,0,1]
	v_pk_fma_f32 v[110:111], v[184:185], s[0:1], v[110:111] op_sel_hi:[1,0,1]
	v_pk_mul_f32 v[108:109], v[108:109], v[158:159]
	v_pk_mul_f32 v[106:107], v[106:107], v[156:157]
	v_pk_fma_f32 v[108:109], v[190:191], s[0:1], v[108:109] op_sel_hi:[1,0,1]
	v_pk_fma_f32 v[106:107], v[188:189], s[0:1], v[106:107] op_sel_hi:[1,0,1]
	v_pk_mul_f32 v[104:105], v[104:105], v[162:163]
	v_pk_mul_f32 v[102:103], v[102:103], v[160:161]
	v_pk_fma_f32 v[104:105], v[194:195], s[0:1], v[104:105] op_sel_hi:[1,0,1]
	v_pk_fma_f32 v[102:103], v[192:193], s[0:1], v[102:103] op_sel_hi:[1,0,1]
	v_pk_mul_f32 v[100:101], v[100:101], v[166:167]
	v_pk_mul_f32 v[98:99], v[98:99], v[164:165]
	v_pk_fma_f32 v[100:101], v[204:205], s[0:1], v[100:101] op_sel_hi:[1,0,1]
	v_pk_fma_f32 v[98:99], v[202:203], s[0:1], v[98:99] op_sel_hi:[1,0,1]
	v_add_u32_e32 v147, 0x80000, v144
	global_load_dwordx4 v[184:187], v147, s[28:29]
	global_load_dwordx4 v[188:191], v147, s[28:29] offset:16
	global_load_dwordx4 v[192:195], v147, s[28:29] offset:512
	global_load_dwordx4 v[202:205], v147, s[28:29] offset:528
	s_waitcnt vmcnt(8)
	v_pk_mul_f32 v[96:97], v[96:97], v[154:155]
	v_pk_mul_f32 v[94:95], v[94:95], v[152:153]
	v_pk_fma_f32 v[96:97], v[208:209], s[0:1], v[96:97] op_sel_hi:[1,0,1]
	v_pk_fma_f32 v[94:95], v[206:207], s[0:1], v[94:95] op_sel_hi:[1,0,1]
	v_pk_mul_f32 v[92:93], v[92:93], v[158:159]
	v_pk_mul_f32 v[90:91], v[90:91], v[156:157]
	v_pk_fma_f32 v[92:93], v[212:213], s[0:1], v[92:93] op_sel_hi:[1,0,1]
	v_pk_fma_f32 v[90:91], v[210:211], s[0:1], v[90:91] op_sel_hi:[1,0,1]
	v_pk_mul_f32 v[88:89], v[88:89], v[162:163]
	v_pk_mul_f32 v[86:87], v[86:87], v[160:161]
	v_pk_fma_f32 v[88:89], v[216:217], s[0:1], v[88:89] op_sel_hi:[1,0,1]
	v_pk_fma_f32 v[86:87], v[214:215], s[0:1], v[86:87] op_sel_hi:[1,0,1]
	v_pk_mul_f32 v[84:85], v[84:85], v[166:167]
	v_pk_mul_f32 v[82:83], v[82:83], v[164:165]
	v_pk_fma_f32 v[84:85], v[220:221], s[0:1], v[84:85] op_sel_hi:[1,0,1]
	v_pk_fma_f32 v[82:83], v[218:219], s[0:1], v[82:83] op_sel_hi:[1,0,1]
	v_add_u32_e32 v147, 0x90000, v144
	global_load_dwordx4 v[206:209], v147, s[28:29]
	global_load_dwordx4 v[210:213], v147, s[28:29] offset:16
	global_load_dwordx4 v[214:217], v147, s[28:29] offset:512
	global_load_dwordx4 v[218:221], v147, s[28:29] offset:528
	s_waitcnt vmcnt(8)
	v_pk_mul_f32 v[80:81], v[80:81], v[154:155]
	v_pk_mul_f32 v[78:79], v[78:79], v[152:153]
	v_pk_fma_f32 v[80:81], v[170:171], s[0:1], v[80:81] op_sel_hi:[1,0,1]
	v_pk_fma_f32 v[78:79], v[168:169], s[0:1], v[78:79] op_sel_hi:[1,0,1]
	v_pk_mul_f32 v[76:77], v[76:77], v[158:159]
	v_pk_mul_f32 v[74:75], v[74:75], v[156:157]
	v_pk_fma_f32 v[76:77], v[174:175], s[0:1], v[76:77] op_sel_hi:[1,0,1]
	v_pk_fma_f32 v[74:75], v[172:173], s[0:1], v[74:75] op_sel_hi:[1,0,1]
	v_pk_mul_f32 v[72:73], v[72:73], v[162:163]
	v_pk_mul_f32 v[70:71], v[70:71], v[160:161]
	v_pk_fma_f32 v[72:73], v[178:179], s[0:1], v[72:73] op_sel_hi:[1,0,1]
	v_pk_fma_f32 v[70:71], v[176:177], s[0:1], v[70:71] op_sel_hi:[1,0,1]
	v_pk_mul_f32 v[68:69], v[68:69], v[166:167]
	v_pk_mul_f32 v[66:67], v[66:67], v[164:165]
	v_pk_fma_f32 v[68:69], v[182:183], s[0:1], v[68:69] op_sel_hi:[1,0,1]
	v_pk_fma_f32 v[66:67], v[180:181], s[0:1], v[66:67] op_sel_hi:[1,0,1]
	v_add_u32_e32 v147, 0xa0000, v144
	global_load_dwordx4 v[168:171], v147, s[28:29]
	global_load_dwordx4 v[172:175], v147, s[28:29] offset:16
	global_load_dwordx4 v[176:179], v147, s[28:29] offset:512
	global_load_dwordx4 v[180:183], v147, s[28:29] offset:528
	s_waitcnt vmcnt(8)
	v_pk_mul_f32 v[64:65], v[64:65], v[154:155]
	v_pk_mul_f32 v[62:63], v[62:63], v[152:153]
	v_pk_fma_f32 v[64:65], v[186:187], s[0:1], v[64:65] op_sel_hi:[1,0,1]
	v_pk_fma_f32 v[62:63], v[184:185], s[0:1], v[62:63] op_sel_hi:[1,0,1]
	v_pk_mul_f32 v[60:61], v[60:61], v[158:159]
	v_pk_mul_f32 v[58:59], v[58:59], v[156:157]
	v_pk_fma_f32 v[60:61], v[190:191], s[0:1], v[60:61] op_sel_hi:[1,0,1]
	v_pk_fma_f32 v[58:59], v[188:189], s[0:1], v[58:59] op_sel_hi:[1,0,1]
	v_pk_mul_f32 v[56:57], v[56:57], v[162:163]
	v_pk_mul_f32 v[54:55], v[54:55], v[160:161]
	v_pk_fma_f32 v[56:57], v[194:195], s[0:1], v[56:57] op_sel_hi:[1,0,1]
	v_pk_fma_f32 v[54:55], v[192:193], s[0:1], v[54:55] op_sel_hi:[1,0,1]
	v_pk_mul_f32 v[52:53], v[52:53], v[166:167]
	v_pk_mul_f32 v[50:51], v[50:51], v[164:165]
	v_pk_fma_f32 v[52:53], v[204:205], s[0:1], v[52:53] op_sel_hi:[1,0,1]
	v_pk_fma_f32 v[50:51], v[202:203], s[0:1], v[50:51] op_sel_hi:[1,0,1]
	v_add_u32_e32 v147, 0xb0000, v144
	global_load_dwordx4 v[184:187], v147, s[28:29]
	global_load_dwordx4 v[188:191], v147, s[28:29] offset:16
	global_load_dwordx4 v[192:195], v147, s[28:29] offset:512
	global_load_dwordx4 v[202:205], v147, s[28:29] offset:528
	s_waitcnt vmcnt(8)
	v_pk_mul_f32 v[48:49], v[48:49], v[154:155]
	v_pk_mul_f32 v[46:47], v[46:47], v[152:153]
	v_pk_fma_f32 v[48:49], v[208:209], s[0:1], v[48:49] op_sel_hi:[1,0,1]
	v_pk_fma_f32 v[46:47], v[206:207], s[0:1], v[46:47] op_sel_hi:[1,0,1]
	v_pk_mul_f32 v[44:45], v[44:45], v[158:159]
	v_pk_mul_f32 v[42:43], v[42:43], v[156:157]
	v_pk_fma_f32 v[44:45], v[212:213], s[0:1], v[44:45] op_sel_hi:[1,0,1]
	v_pk_fma_f32 v[42:43], v[210:211], s[0:1], v[42:43] op_sel_hi:[1,0,1]
	v_pk_mul_f32 v[40:41], v[40:41], v[162:163]
	v_pk_mul_f32 v[38:39], v[38:39], v[160:161]
	v_pk_fma_f32 v[40:41], v[216:217], s[0:1], v[40:41] op_sel_hi:[1,0,1]
	v_pk_fma_f32 v[38:39], v[214:215], s[0:1], v[38:39] op_sel_hi:[1,0,1]
	v_pk_mul_f32 v[36:37], v[36:37], v[166:167]
	v_pk_mul_f32 v[34:35], v[34:35], v[164:165]
	v_pk_fma_f32 v[36:37], v[220:221], s[0:1], v[36:37] op_sel_hi:[1,0,1]
	v_pk_fma_f32 v[34:35], v[218:219], s[0:1], v[34:35] op_sel_hi:[1,0,1]
	s_waitcnt vmcnt(4)
	v_pk_mul_f32 v[32:33], v[32:33], v[154:155]
	v_pk_mul_f32 v[30:31], v[30:31], v[152:153]
	v_pk_fma_f32 v[32:33], v[170:171], s[0:1], v[32:33] op_sel_hi:[1,0,1]
	v_pk_fma_f32 v[30:31], v[168:169], s[0:1], v[30:31] op_sel_hi:[1,0,1]
	v_pk_mul_f32 v[28:29], v[28:29], v[158:159]
	v_pk_mul_f32 v[26:27], v[26:27], v[156:157]
	v_pk_fma_f32 v[28:29], v[174:175], s[0:1], v[28:29] op_sel_hi:[1,0,1]
	v_pk_fma_f32 v[26:27], v[172:173], s[0:1], v[26:27] op_sel_hi:[1,0,1]
	v_pk_mul_f32 v[24:25], v[24:25], v[162:163]
	v_pk_mul_f32 v[22:23], v[22:23], v[160:161]
	v_pk_fma_f32 v[24:25], v[178:179], s[0:1], v[24:25] op_sel_hi:[1,0,1]
	v_pk_fma_f32 v[22:23], v[176:177], s[0:1], v[22:23] op_sel_hi:[1,0,1]
	v_pk_mul_f32 v[20:21], v[20:21], v[166:167]
	v_pk_mul_f32 v[18:19], v[18:19], v[164:165]
	v_pk_fma_f32 v[20:21], v[182:183], s[0:1], v[20:21] op_sel_hi:[1,0,1]
	v_pk_fma_f32 v[18:19], v[180:181], s[0:1], v[18:19] op_sel_hi:[1,0,1]
	s_waitcnt vmcnt(0)
	v_pk_mul_f32 v[16:17], v[16:17], v[154:155]
	v_pk_mul_f32 v[14:15], v[14:15], v[152:153]
	v_pk_fma_f32 v[16:17], v[186:187], s[0:1], v[16:17] op_sel_hi:[1,0,1]
	v_pk_fma_f32 v[14:15], v[184:185], s[0:1], v[14:15] op_sel_hi:[1,0,1]
	v_pk_mul_f32 v[12:13], v[12:13], v[158:159]
	v_pk_mul_f32 v[10:11], v[10:11], v[156:157]
	v_pk_fma_f32 v[12:13], v[190:191], s[0:1], v[12:13] op_sel_hi:[1,0,1]
	v_pk_fma_f32 v[10:11], v[188:189], s[0:1], v[10:11] op_sel_hi:[1,0,1]
	v_pk_mul_f32 v[8:9], v[8:9], v[162:163]
	v_pk_mul_f32 v[6:7], v[6:7], v[160:161]
	v_pk_fma_f32 v[8:9], v[194:195], s[0:1], v[8:9] op_sel_hi:[1,0,1]
	v_pk_fma_f32 v[6:7], v[192:193], s[0:1], v[6:7] op_sel_hi:[1,0,1]
	v_pk_mul_f32 v[4:5], v[4:5], v[166:167]
	v_pk_mul_f32 v[2:3], v[2:3], v[164:165]
	v_pk_fma_f32 v[4:5], v[204:205], s[0:1], v[4:5] op_sel_hi:[1,0,1]
	v_pk_fma_f32 v[2:3], v[202:203], s[0:1], v[2:3] op_sel_hi:[1,0,1]
	s_barrier
	s_and_b32 s1, s21, 0xc0
	v_and_b32_e32 v0, 15, v230
	v_add_u32_e32 v147, s1, v0
	s_lshr_b32 s1, s91, 6
	s_and_b32 s1, s1, 3
	s_lshl_b32 s1, s1, 2
	v_lshlrev_b32_e32 v148, 4, v147
	v_add_u32_e32 v148, s1, v148
	v_or_b32_e32 v149, s91, v230
	v_and_b32_e32 v149, 0xff, v149
	v_pk_add_f32 v[202:203], v[126:127], v[128:129]
	v_pk_add_f32 v[202:203], v[202:203], v[122:123]
	v_pk_add_f32 v[202:203], v[202:203], v[124:125]
	v_pk_add_f32 v[202:203], v[202:203], v[118:119]
	v_pk_add_f32 v[202:203], v[202:203], v[120:121]
	v_pk_add_f32 v[202:203], v[202:203], v[114:115]
	v_pk_add_f32 v[202:203], v[202:203], v[116:117]
	v_pk_add_f32 v[204:205], v[110:111], v[112:113]
	v_pk_add_f32 v[204:205], v[204:205], v[106:107]
	v_pk_add_f32 v[204:205], v[204:205], v[108:109]
	v_pk_add_f32 v[204:205], v[204:205], v[102:103]
	v_pk_add_f32 v[204:205], v[204:205], v[104:105]
	v_pk_add_f32 v[204:205], v[204:205], v[98:99]
	v_pk_add_f32 v[204:205], v[204:205], v[100:101]
	v_pk_add_f32 v[206:207], v[94:95], v[96:97]
	v_pk_add_f32 v[206:207], v[206:207], v[90:91]
	v_pk_add_f32 v[206:207], v[206:207], v[92:93]
	v_pk_add_f32 v[206:207], v[206:207], v[86:87]
	v_pk_add_f32 v[206:207], v[206:207], v[88:89]
	v_pk_add_f32 v[206:207], v[206:207], v[82:83]
	v_pk_add_f32 v[206:207], v[206:207], v[84:85]
	v_pk_add_f32 v[208:209], v[78:79], v[80:81]
	v_pk_add_f32 v[208:209], v[208:209], v[74:75]
	v_pk_add_f32 v[208:209], v[208:209], v[76:77]
	v_pk_add_f32 v[208:209], v[208:209], v[70:71]
	v_pk_add_f32 v[208:209], v[208:209], v[72:73]
	v_pk_add_f32 v[208:209], v[208:209], v[66:67]
	v_pk_add_f32 v[208:209], v[208:209], v[68:69]
	v_pk_add_f32 v[210:211], v[62:63], v[64:65]
	v_pk_add_f32 v[210:211], v[210:211], v[58:59]
	v_pk_add_f32 v[210:211], v[210:211], v[60:61]
	v_pk_add_f32 v[210:211], v[210:211], v[54:55]
	v_pk_add_f32 v[210:211], v[210:211], v[56:57]
	v_pk_add_f32 v[210:211], v[210:211], v[50:51]
	v_pk_add_f32 v[210:211], v[210:211], v[52:53]
	v_pk_add_f32 v[212:213], v[46:47], v[48:49]
	v_pk_add_f32 v[212:213], v[212:213], v[42:43]
	v_pk_add_f32 v[212:213], v[212:213], v[44:45]
	v_pk_add_f32 v[212:213], v[212:213], v[38:39]
	v_pk_add_f32 v[212:213], v[212:213], v[40:41]
	v_pk_add_f32 v[212:213], v[212:213], v[34:35]
	v_pk_add_f32 v[212:213], v[212:213], v[36:37]
	v_pk_add_f32 v[214:215], v[30:31], v[32:33]
	v_pk_add_f32 v[214:215], v[214:215], v[26:27]
	v_pk_add_f32 v[214:215], v[214:215], v[28:29]
	v_pk_add_f32 v[214:215], v[214:215], v[22:23]
	v_pk_add_f32 v[214:215], v[214:215], v[24:25]
	v_pk_add_f32 v[214:215], v[214:215], v[18:19]
	v_pk_add_f32 v[214:215], v[214:215], v[20:21]
	v_pk_add_f32 v[216:217], v[14:15], v[16:17]
	v_pk_add_f32 v[216:217], v[216:217], v[10:11]
	v_pk_add_f32 v[216:217], v[216:217], v[12:13]
	v_pk_add_f32 v[216:217], v[216:217], v[6:7]
	v_pk_add_f32 v[216:217], v[216:217], v[8:9]
	v_pk_add_f32 v[216:217], v[216:217], v[2:3]
	v_pk_add_f32 v[216:217], v[216:217], v[4:5]
	v_add_f32_e32 v202, v202, v203
	v_add_f32_e32 v204, v204, v205
	v_add_f32_e32 v206, v206, v207
	v_add_f32_e32 v208, v208, v209
	v_add_f32_e32 v210, v210, v211
	v_add_f32_e32 v212, v212, v213
	v_add_f32_e32 v214, v214, v215
	v_add_f32_e32 v216, v216, v217
	v_mov_b32_e32 v203, v202
	v_mov_b32_e32 v205, v204
	v_mov_b32_e32 v207, v206
	v_mov_b32_e32 v209, v208
	v_mov_b32_e32 v211, v210
	v_mov_b32_e32 v213, v212
	v_mov_b32_e32 v215, v214
	v_mov_b32_e32 v217, v216
	v_permlane16_swap_b32_e32 v202, v203
	v_permlane16_swap_b32_e32 v204, v205
	v_permlane16_swap_b32_e32 v206, v207
	v_permlane16_swap_b32_e32 v208, v209
	v_permlane16_swap_b32_e32 v210, v211
	v_permlane16_swap_b32_e32 v212, v213
	v_permlane16_swap_b32_e32 v214, v215
	v_permlane16_swap_b32_e32 v216, v217
	v_add_f32_e32 v202, v202, v203
	v_add_f32_e32 v204, v204, v205
	v_add_f32_e32 v206, v206, v207
	v_add_f32_e32 v208, v208, v209
	v_add_f32_e32 v210, v210, v211
	v_add_f32_e32 v212, v212, v213
	v_add_f32_e32 v214, v214, v215
	v_add_f32_e32 v216, v216, v217
	v_mov_b32_e32 v203, v202
	v_mov_b32_e32 v205, v204
	v_mov_b32_e32 v207, v206
	v_mov_b32_e32 v209, v208
	v_mov_b32_e32 v211, v210
	v_mov_b32_e32 v213, v212
	v_mov_b32_e32 v215, v214
	v_mov_b32_e32 v217, v216
	v_permlane32_swap_b32_e32 v202, v203
	v_permlane32_swap_b32_e32 v204, v205
	v_permlane32_swap_b32_e32 v206, v207
	v_permlane32_swap_b32_e32 v208, v209
	v_permlane32_swap_b32_e32 v210, v211
	v_permlane32_swap_b32_e32 v212, v213
	v_permlane32_swap_b32_e32 v214, v215
	v_permlane32_swap_b32_e32 v216, v217
	v_add_f32_e32 v202, v202, v203
	v_add_f32_e32 v204, v204, v205
	v_add_f32_e32 v206, v206, v207
	v_add_f32_e32 v208, v208, v209
	v_add_f32_e32 v210, v210, v211
	v_add_f32_e32 v212, v212, v213
	v_add_f32_e32 v214, v214, v215
	v_add_f32_e32 v216, v216, v217
	s_mov_b32 s0, 0xffff
	s_mov_b32 s1, 0
	s_mov_b64 exec, s[0:1]
	ds_write_b32 v148, v202 offset:0
	ds_write_b32 v148, v204 offset:256
	s_lshl_b64 exec, s[0:1], 16
	ds_write_b32 v148, v206 offset:512
	ds_write_b32 v148, v208 offset:768
	s_lshl_b64 exec, s[0:1], 32
	ds_write_b32 v148, v210 offset:2048
	ds_write_b32 v148, v212 offset:2304
	s_lshl_b64 exec, s[0:1], 48
	ds_write_b32 v148, v214 offset:2560
	ds_write_b32 v148, v216 offset:2816
	s_mov_b64 exec, -1
	s_waitcnt lgkmcnt(0)
	s_barrier
	v_lshlrev_b32_e32 v0, 4, v149
	ds_read_b128 v[218:221], v0
	s_waitcnt lgkmcnt(0)
	v_add_f32_e32 v218, v218, v219
	v_add_f32_e32 v220, v220, v221
	v_add_f32_e32 v218, v218, v220
	v_mul_f32_e32 v164, 0x3b800000, v218
	v_lshlrev_b32_e32 v0, 2, v149
	ds_write_b32 v0, v164 offset:8192
	s_waitcnt lgkmcnt(0)
	s_barrier
	v_lshlrev_b32_e32 v0, 2, v147
	ds_read_b32 v202, v0 offset:8192
	ds_read_b32 v204, v0 offset:8256
	ds_read_b32 v206, v0 offset:8320
	ds_read_b32 v208, v0 offset:8384
	ds_read_b32 v210, v0 offset:8704
	ds_read_b32 v212, v0 offset:8768
	ds_read_b32 v214, v0 offset:8832
	ds_read_b32 v216, v0 offset:8896
	s_waitcnt lgkmcnt(0)
	v_pk_add_f32 v[218:219], v[126:127], v[202:203] op_sel_hi:[1,0] neg_lo:[0,1] neg_hi:[0,1]
	v_pk_mul_f32 v[166:167], v[218:219], v[218:219]
	v_pk_add_f32 v[218:219], v[128:129], v[202:203] op_sel_hi:[1,0] neg_lo:[0,1] neg_hi:[0,1]
	v_pk_fma_f32 v[166:167], v[218:219], v[218:219], v[166:167]
	v_pk_add_f32 v[218:219], v[122:123], v[202:203] op_sel_hi:[1,0] neg_lo:[0,1] neg_hi:[0,1]
	v_pk_fma_f32 v[166:167], v[218:219], v[218:219], v[166:167]
	v_pk_add_f32 v[218:219], v[124:125], v[202:203] op_sel_hi:[1,0] neg_lo:[0,1] neg_hi:[0,1]
	v_pk_fma_f32 v[166:167], v[218:219], v[218:219], v[166:167]
	v_pk_add_f32 v[218:219], v[118:119], v[202:203] op_sel_hi:[1,0] neg_lo:[0,1] neg_hi:[0,1]
	v_pk_fma_f32 v[166:167], v[218:219], v[218:219], v[166:167]
	v_pk_add_f32 v[218:219], v[120:121], v[202:203] op_sel_hi:[1,0] neg_lo:[0,1] neg_hi:[0,1]
	v_pk_fma_f32 v[166:167], v[218:219], v[218:219], v[166:167]
	v_pk_add_f32 v[218:219], v[114:115], v[202:203] op_sel_hi:[1,0] neg_lo:[0,1] neg_hi:[0,1]
	v_pk_fma_f32 v[166:167], v[218:219], v[218:219], v[166:167]
	v_pk_add_f32 v[218:219], v[116:117], v[202:203] op_sel_hi:[1,0] neg_lo:[0,1] neg_hi:[0,1]
	v_pk_fma_f32 v[166:167], v[218:219], v[218:219], v[166:167]
	v_pk_add_f32 v[218:219], v[110:111], v[204:205] op_sel_hi:[1,0] neg_lo:[0,1] neg_hi:[0,1]
	v_pk_mul_f32 v[168:169], v[218:219], v[218:219]
	v_pk_add_f32 v[218:219], v[112:113], v[204:205] op_sel_hi:[1,0] neg_lo:[0,1] neg_hi:[0,1]
	v_pk_fma_f32 v[168:169], v[218:219], v[218:219], v[168:169]
	v_pk_add_f32 v[218:219], v[106:107], v[204:205] op_sel_hi:[1,0] neg_lo:[0,1] neg_hi:[0,1]
	v_pk_fma_f32 v[168:169], v[218:219], v[218:219], v[168:169]
	v_pk_add_f32 v[218:219], v[108:109], v[204:205] op_sel_hi:[1,0] neg_lo:[0,1] neg_hi:[0,1]
	v_pk_fma_f32 v[168:169], v[218:219], v[218:219], v[168:169]
	v_pk_add_f32 v[218:219], v[102:103], v[204:205] op_sel_hi:[1,0] neg_lo:[0,1] neg_hi:[0,1]
	v_pk_fma_f32 v[168:169], v[218:219], v[218:219], v[168:169]
	v_pk_add_f32 v[218:219], v[104:105], v[204:205] op_sel_hi:[1,0] neg_lo:[0,1] neg_hi:[0,1]
	v_pk_fma_f32 v[168:169], v[218:219], v[218:219], v[168:169]
	v_pk_add_f32 v[218:219], v[98:99], v[204:205] op_sel_hi:[1,0] neg_lo:[0,1] neg_hi:[0,1]
	v_pk_fma_f32 v[168:169], v[218:219], v[218:219], v[168:169]
	v_pk_add_f32 v[218:219], v[100:101], v[204:205] op_sel_hi:[1,0] neg_lo:[0,1] neg_hi:[0,1]
	v_pk_fma_f32 v[168:169], v[218:219], v[218:219], v[168:169]
	v_pk_add_f32 v[218:219], v[94:95], v[206:207] op_sel_hi:[1,0] neg_lo:[0,1] neg_hi:[0,1]
	v_pk_mul_f32 v[170:171], v[218:219], v[218:219]
	v_pk_add_f32 v[218:219], v[96:97], v[206:207] op_sel_hi:[1,0] neg_lo:[0,1] neg_hi:[0,1]
	v_pk_fma_f32 v[170:171], v[218:219], v[218:219], v[170:171]
	v_pk_add_f32 v[218:219], v[90:91], v[206:207] op_sel_hi:[1,0] neg_lo:[0,1] neg_hi:[0,1]
	v_pk_fma_f32 v[170:171], v[218:219], v[218:219], v[170:171]
	v_pk_add_f32 v[218:219], v[92:93], v[206:207] op_sel_hi:[1,0] neg_lo:[0,1] neg_hi:[0,1]
	v_pk_fma_f32 v[170:171], v[218:219], v[218:219], v[170:171]
	v_pk_add_f32 v[218:219], v[86:87], v[206:207] op_sel_hi:[1,0] neg_lo:[0,1] neg_hi:[0,1]
	v_pk_fma_f32 v[170:171], v[218:219], v[218:219], v[170:171]
	v_pk_add_f32 v[218:219], v[88:89], v[206:207] op_sel_hi:[1,0] neg_lo:[0,1] neg_hi:[0,1]
	v_pk_fma_f32 v[170:171], v[218:219], v[218:219], v[170:171]
	v_pk_add_f32 v[218:219], v[82:83], v[206:207] op_sel_hi:[1,0] neg_lo:[0,1] neg_hi:[0,1]
	v_pk_fma_f32 v[170:171], v[218:219], v[218:219], v[170:171]
	v_pk_add_f32 v[218:219], v[84:85], v[206:207] op_sel_hi:[1,0] neg_lo:[0,1] neg_hi:[0,1]
	v_pk_fma_f32 v[170:171], v[218:219], v[218:219], v[170:171]
	v_pk_add_f32 v[218:219], v[78:79], v[208:209] op_sel_hi:[1,0] neg_lo:[0,1] neg_hi:[0,1]
	v_pk_mul_f32 v[172:173], v[218:219], v[218:219]
	v_pk_add_f32 v[218:219], v[80:81], v[208:209] op_sel_hi:[1,0] neg_lo:[0,1] neg_hi:[0,1]
	v_pk_fma_f32 v[172:173], v[218:219], v[218:219], v[172:173]
	v_pk_add_f32 v[218:219], v[74:75], v[208:209] op_sel_hi:[1,0] neg_lo:[0,1] neg_hi:[0,1]
	v_pk_fma_f32 v[172:173], v[218:219], v[218:219], v[172:173]
	v_pk_add_f32 v[218:219], v[76:77], v[208:209] op_sel_hi:[1,0] neg_lo:[0,1] neg_hi:[0,1]
	v_pk_fma_f32 v[172:173], v[218:219], v[218:219], v[172:173]
	v_pk_add_f32 v[218:219], v[70:71], v[208:209] op_sel_hi:[1,0] neg_lo:[0,1] neg_hi:[0,1]
	v_pk_fma_f32 v[172:173], v[218:219], v[218:219], v[172:173]
	v_pk_add_f32 v[218:219], v[72:73], v[208:209] op_sel_hi:[1,0] neg_lo:[0,1] neg_hi:[0,1]
	v_pk_fma_f32 v[172:173], v[218:219], v[218:219], v[172:173]
	v_pk_add_f32 v[218:219], v[66:67], v[208:209] op_sel_hi:[1,0] neg_lo:[0,1] neg_hi:[0,1]
	v_pk_fma_f32 v[172:173], v[218:219], v[218:219], v[172:173]
	v_pk_add_f32 v[218:219], v[68:69], v[208:209] op_sel_hi:[1,0] neg_lo:[0,1] neg_hi:[0,1]
	v_pk_fma_f32 v[172:173], v[218:219], v[218:219], v[172:173]
	v_pk_add_f32 v[218:219], v[62:63], v[210:211] op_sel_hi:[1,0] neg_lo:[0,1] neg_hi:[0,1]
	v_pk_mul_f32 v[174:175], v[218:219], v[218:219]
	v_pk_add_f32 v[218:219], v[64:65], v[210:211] op_sel_hi:[1,0] neg_lo:[0,1] neg_hi:[0,1]
	v_pk_fma_f32 v[174:175], v[218:219], v[218:219], v[174:175]
	v_pk_add_f32 v[218:219], v[58:59], v[210:211] op_sel_hi:[1,0] neg_lo:[0,1] neg_hi:[0,1]
	v_pk_fma_f32 v[174:175], v[218:219], v[218:219], v[174:175]
	v_pk_add_f32 v[218:219], v[60:61], v[210:211] op_sel_hi:[1,0] neg_lo:[0,1] neg_hi:[0,1]
	v_pk_fma_f32 v[174:175], v[218:219], v[218:219], v[174:175]
	v_pk_add_f32 v[218:219], v[54:55], v[210:211] op_sel_hi:[1,0] neg_lo:[0,1] neg_hi:[0,1]
	v_pk_fma_f32 v[174:175], v[218:219], v[218:219], v[174:175]
	v_pk_add_f32 v[218:219], v[56:57], v[210:211] op_sel_hi:[1,0] neg_lo:[0,1] neg_hi:[0,1]
	v_pk_fma_f32 v[174:175], v[218:219], v[218:219], v[174:175]
	v_pk_add_f32 v[218:219], v[50:51], v[210:211] op_sel_hi:[1,0] neg_lo:[0,1] neg_hi:[0,1]
	v_pk_fma_f32 v[174:175], v[218:219], v[218:219], v[174:175]
	v_pk_add_f32 v[218:219], v[52:53], v[210:211] op_sel_hi:[1,0] neg_lo:[0,1] neg_hi:[0,1]
	v_pk_fma_f32 v[174:175], v[218:219], v[218:219], v[174:175]
	v_pk_add_f32 v[218:219], v[46:47], v[212:213] op_sel_hi:[1,0] neg_lo:[0,1] neg_hi:[0,1]
	v_pk_mul_f32 v[176:177], v[218:219], v[218:219]
	v_pk_add_f32 v[218:219], v[48:49], v[212:213] op_sel_hi:[1,0] neg_lo:[0,1] neg_hi:[0,1]
	v_pk_fma_f32 v[176:177], v[218:219], v[218:219], v[176:177]
	v_pk_add_f32 v[218:219], v[42:43], v[212:213] op_sel_hi:[1,0] neg_lo:[0,1] neg_hi:[0,1]
	v_pk_fma_f32 v[176:177], v[218:219], v[218:219], v[176:177]
	v_pk_add_f32 v[218:219], v[44:45], v[212:213] op_sel_hi:[1,0] neg_lo:[0,1] neg_hi:[0,1]
	v_pk_fma_f32 v[176:177], v[218:219], v[218:219], v[176:177]
	v_pk_add_f32 v[218:219], v[38:39], v[212:213] op_sel_hi:[1,0] neg_lo:[0,1] neg_hi:[0,1]
	v_pk_fma_f32 v[176:177], v[218:219], v[218:219], v[176:177]
	v_pk_add_f32 v[218:219], v[40:41], v[212:213] op_sel_hi:[1,0] neg_lo:[0,1] neg_hi:[0,1]
	v_pk_fma_f32 v[176:177], v[218:219], v[218:219], v[176:177]
	v_pk_add_f32 v[218:219], v[34:35], v[212:213] op_sel_hi:[1,0] neg_lo:[0,1] neg_hi:[0,1]
	v_pk_fma_f32 v[176:177], v[218:219], v[218:219], v[176:177]
	v_pk_add_f32 v[218:219], v[36:37], v[212:213] op_sel_hi:[1,0] neg_lo:[0,1] neg_hi:[0,1]
	v_pk_fma_f32 v[176:177], v[218:219], v[218:219], v[176:177]
	v_pk_add_f32 v[218:219], v[30:31], v[214:215] op_sel_hi:[1,0] neg_lo:[0,1] neg_hi:[0,1]
	v_pk_mul_f32 v[178:179], v[218:219], v[218:219]
	v_pk_add_f32 v[218:219], v[32:33], v[214:215] op_sel_hi:[1,0] neg_lo:[0,1] neg_hi:[0,1]
	v_pk_fma_f32 v[178:179], v[218:219], v[218:219], v[178:179]
	v_pk_add_f32 v[218:219], v[26:27], v[214:215] op_sel_hi:[1,0] neg_lo:[0,1] neg_hi:[0,1]
	v_pk_fma_f32 v[178:179], v[218:219], v[218:219], v[178:179]
	v_pk_add_f32 v[218:219], v[28:29], v[214:215] op_sel_hi:[1,0] neg_lo:[0,1] neg_hi:[0,1]
	v_pk_fma_f32 v[178:179], v[218:219], v[218:219], v[178:179]
	v_pk_add_f32 v[218:219], v[22:23], v[214:215] op_sel_hi:[1,0] neg_lo:[0,1] neg_hi:[0,1]
	v_pk_fma_f32 v[178:179], v[218:219], v[218:219], v[178:179]
	v_pk_add_f32 v[218:219], v[24:25], v[214:215] op_sel_hi:[1,0] neg_lo:[0,1] neg_hi:[0,1]
	v_pk_fma_f32 v[178:179], v[218:219], v[218:219], v[178:179]
	v_pk_add_f32 v[218:219], v[18:19], v[214:215] op_sel_hi:[1,0] neg_lo:[0,1] neg_hi:[0,1]
	v_pk_fma_f32 v[178:179], v[218:219], v[218:219], v[178:179]
	v_pk_add_f32 v[218:219], v[20:21], v[214:215] op_sel_hi:[1,0] neg_lo:[0,1] neg_hi:[0,1]
	v_pk_fma_f32 v[178:179], v[218:219], v[218:219], v[178:179]
	v_pk_add_f32 v[218:219], v[14:15], v[216:217] op_sel_hi:[1,0] neg_lo:[0,1] neg_hi:[0,1]
	v_pk_mul_f32 v[180:181], v[218:219], v[218:219]
	v_pk_add_f32 v[218:219], v[16:17], v[216:217] op_sel_hi:[1,0] neg_lo:[0,1] neg_hi:[0,1]
	v_pk_fma_f32 v[180:181], v[218:219], v[218:219], v[180:181]
	v_pk_add_f32 v[218:219], v[10:11], v[216:217] op_sel_hi:[1,0] neg_lo:[0,1] neg_hi:[0,1]
	v_pk_fma_f32 v[180:181], v[218:219], v[218:219], v[180:181]
	v_pk_add_f32 v[218:219], v[12:13], v[216:217] op_sel_hi:[1,0] neg_lo:[0,1] neg_hi:[0,1]
	v_pk_fma_f32 v[180:181], v[218:219], v[218:219], v[180:181]
	v_pk_add_f32 v[218:219], v[6:7], v[216:217] op_sel_hi:[1,0] neg_lo:[0,1] neg_hi:[0,1]
	v_pk_fma_f32 v[180:181], v[218:219], v[218:219], v[180:181]
	v_pk_add_f32 v[218:219], v[8:9], v[216:217] op_sel_hi:[1,0] neg_lo:[0,1] neg_hi:[0,1]
	v_pk_fma_f32 v[180:181], v[218:219], v[218:219], v[180:181]
	v_pk_add_f32 v[218:219], v[2:3], v[216:217] op_sel_hi:[1,0] neg_lo:[0,1] neg_hi:[0,1]
	v_pk_fma_f32 v[180:181], v[218:219], v[218:219], v[180:181]
	v_pk_add_f32 v[218:219], v[4:5], v[216:217] op_sel_hi:[1,0] neg_lo:[0,1] neg_hi:[0,1]
	v_pk_fma_f32 v[180:181], v[218:219], v[218:219], v[180:181]
	v_add_f32_e32 v166, v166, v167
	v_add_f32_e32 v168, v168, v169
	v_add_f32_e32 v170, v170, v171
	v_add_f32_e32 v172, v172, v173
	v_add_f32_e32 v174, v174, v175
	v_add_f32_e32 v176, v176, v177
	v_add_f32_e32 v178, v178, v179
	v_add_f32_e32 v180, v180, v181
	v_mov_b32_e32 v167, v166
	v_mov_b32_e32 v169, v168
	v_mov_b32_e32 v171, v170
	v_mov_b32_e32 v173, v172
	v_mov_b32_e32 v175, v174
	v_mov_b32_e32 v177, v176
	v_mov_b32_e32 v179, v178
	v_mov_b32_e32 v181, v180
	v_permlane16_swap_b32_e32 v166, v167
	v_permlane16_swap_b32_e32 v168, v169
	v_permlane16_swap_b32_e32 v170, v171
	v_permlane16_swap_b32_e32 v172, v173
	v_permlane16_swap_b32_e32 v174, v175
	v_permlane16_swap_b32_e32 v176, v177
	v_permlane16_swap_b32_e32 v178, v179
	v_permlane16_swap_b32_e32 v180, v181
	v_add_f32_e32 v166, v166, v167
	v_add_f32_e32 v168, v168, v169
	v_add_f32_e32 v170, v170, v171
	v_add_f32_e32 v172, v172, v173
	v_add_f32_e32 v174, v174, v175
	v_add_f32_e32 v176, v176, v177
	v_add_f32_e32 v178, v178, v179
	v_add_f32_e32 v180, v180, v181
	v_mov_b32_e32 v167, v166
	v_mov_b32_e32 v169, v168
	v_mov_b32_e32 v171, v170
	v_mov_b32_e32 v173, v172
	v_mov_b32_e32 v175, v174
	v_mov_b32_e32 v177, v176
	v_mov_b32_e32 v179, v178
	v_mov_b32_e32 v181, v180
	v_permlane32_swap_b32_e32 v166, v167
	v_permlane32_swap_b32_e32 v168, v169
	v_permlane32_swap_b32_e32 v170, v171
	v_permlane32_swap_b32_e32 v172, v173
	v_permlane32_swap_b32_e32 v174, v175
	v_permlane32_swap_b32_e32 v176, v177
	v_permlane32_swap_b32_e32 v178, v179
	v_permlane32_swap_b32_e32 v180, v181
	v_add_f32_e32 v166, v166, v167
	v_add_f32_e32 v168, v168, v169
	v_add_f32_e32 v170, v170, v171
	v_add_f32_e32 v172, v172, v173
	v_add_f32_e32 v174, v174, v175
	v_add_f32_e32 v176, v176, v177
	v_add_f32_e32 v178, v178, v179
	v_add_f32_e32 v180, v180, v181
	s_mov_b32 s0, 0xffff
	s_mov_b32 s1, 0
	s_mov_b64 exec, s[0:1]
	ds_write_b32 v148, v166 offset:4096
	ds_write_b32 v148, v168 offset:4352
	s_lshl_b64 exec, s[0:1], 16
	ds_write_b32 v148, v170 offset:4608
	ds_write_b32 v148, v172 offset:4864
	s_lshl_b64 exec, s[0:1], 32
	ds_write_b32 v148, v174 offset:6144
	ds_write_b32 v148, v176 offset:6400
	s_lshl_b64 exec, s[0:1], 48
	ds_write_b32 v148, v178 offset:6656
	ds_write_b32 v148, v180 offset:6912
	s_mov_b64 exec, -1
	s_waitcnt lgkmcnt(0)
	s_barrier
	v_lshlrev_b32_e32 v0, 4, v149
	ds_read_b128 v[218:221], v0 offset:4096
	s_waitcnt lgkmcnt(0)
	v_add_f32_e32 v218, v218, v219
	v_add_f32_e32 v220, v220, v221
	v_add_f32_e32 v165, v218, v220
	s_mov_b32 s0, 0
	s_mov_b32 s1, s71
	s_xor_b64 s[0:1], s[0:1], s[62:63]
	s_lshr_b32 s8, s21, 8
	s_lshl_b32 s9, s8, 13
	s_add_u32 s30, s0, s9
	s_addc_u32 s31, s1, 0
	s_add_u32 s30, s30, 0xb23e000
	s_addc_u32 s31, s31, 0
	s_lshl_b32 s9, s23, 3
	s_add_u32 s28, s30, s9
	s_addc_u32 s29, s31, 0
	s_mov_b32 s23, s52
	v_readlane_b32 s8, v251, 0
	v_readlane_b32 s9, v251, 1
	v_readlane_b32 s37, v254, 53
	s_nop 4
	s_load_dwordx4 s[52:55], s[8:9], 0xb8
	s_load_dwordx2 s[38:39], s[8:9], 0xe8
	s_lshl_b32 s8, s37, 12
	s_waitcnt lgkmcnt(0)
	s_add_u32 s52, s52, s8
	s_addc_u32 s53, s53, 0
	s_add_u32 s54, s54, s8
	s_addc_u32 s55, s55, 0
	global_load_dwordx4 v[174:177], v146, s[52:53]
	global_load_dwordx4 v[178:181], v146, s[52:53] offset:16
	global_load_dwordx4 v[182:185], v146, s[52:53] offset:512
	global_load_dwordx4 v[186:189], v146, s[52:53] offset:528
	global_load_dwordx4 v[190:193], v146, s[54:55]
	global_load_dwordx4 v[194:197], v146, s[54:55] offset:16
	global_load_dwordx4 v[202:205], v146, s[54:55] offset:512
	global_load_dwordx4 v[206:209], v146, s[54:55] offset:528
	v_lshlrev_b32_e32 v0, 5, v149
	s_cmp_lt_u32 s91, 0x100
	s_cbranch_scc0 .Lg3ln_nostore
	global_store_dwordx2 v0, v[164:165], s[28:29] sc1
.Lg3ln_nostore:
	s_waitcnt vmcnt(0)
	s_barrier
	v_or_b32_e32 v218, s91, v230
	v_cmp_eq_u32_e32 vcc, 0, v218
	s_and_saveexec_b64 s[34:35], vcc
	s_cbranch_execz .Lg3ln_joined
	s_lshr_b32 s8, s21, 8
	s_lshl_b32 s9, s37, 5
	s_add_i32 s9, s9, s8
	s_lshl_b32 s9, s9, 2
	s_add_i32 s9, s9, 0x2800
	v_mov_b32_e32 v218, s9
	s_add_u32 s8, s0, 0xee3e000
	s_addc_u32 s9, s1, 0
	v_mov_b32_e32 v219, 1
	v_mov_b32_e32 v221, 0
	global_atomic_add v218, v219, s[8:9]
.Lg3ln_poll:
	global_load_dword v220, v218, s[8:9] sc1
	s_waitcnt vmcnt(0)
	v_cmp_le_u32_e32 vcc, 4, v220
	s_cbranch_vccnz .Lg3ln_seen
	v_add_u32_e32 v221, 1, v221
	s_sleep 1
	v_cmp_gt_u32_e32 vcc, 0x20000, v221
	s_cbranch_vccnz .Lg3ln_poll
.Lg3ln_seen:
	buffer_inv sc1
	s_waitcnt vmcnt(0)
.Lg3ln_joined:
	s_or_b64 exec, exec, s[34:35]
	s_barrier
	global_load_dwordx4 v[166:169], v0, s[30:31] sc1
	global_load_dwordx4 v[170:173], v0, s[30:31] offset:16 sc1
	s_waitcnt vmcnt(0)
	v_add_f32_e32 v218, v166, v168
	v_add_f32_e32 v219, v170, v172
	v_add_f32_e32 v218, v218, v219
	v_mul_f32_e32 v220, 0x3e800000, v218
	v_sub_f32_e32 v218, v166, v220
	v_mul_f32_e32 v219, v218, v218
	v_sub_f32_e32 v218, v168, v220
	v_fmac_f32_e32 v219, v218, v218
	v_sub_f32_e32 v218, v170, v220
	v_fmac_f32_e32 v219, v218, v218
	v_sub_f32_e32 v218, v172, v220
	v_fmac_f32_e32 v219, v218, v218
	v_add_f32_e32 v218, v167, v169
	v_add_f32_e32 v216, v171, v173
	v_add_f32_e32 v218, v218, v216
	v_fmac_f32_e32 v218, 0x43800000, v219
	v_mov_b32_e32 v216, 0x3727c5ac
	v_fmac_f32_e32 v216, 0x3a800000, v218
	v_rsq_f32_e32 v221, v216
	v_lshlrev_b32_e32 v0, 3, v149
	s_nop 0
	ds_write_b64 v0, v[220:221] offset:9216
	s_waitcnt lgkmcnt(0)
	s_barrier
	v_lshlrev_b32_e32 v0, 3, v147
	ds_read_b64 v[150:151], v0 offset:9216
	ds_read_b64 v[152:153], v0 offset:9344
	ds_read_b64 v[154:155], v0 offset:9472
	ds_read_b64 v[156:157], v0 offset:9600
	ds_read_b64 v[158:159], v0 offset:10240
	ds_read_b64 v[160:161], v0 offset:10368
	ds_read_b64 v[162:163], v0 offset:10496
	ds_read_b64 v[164:165], v0 offset:10624
	s_mov_b32 s0, 0
	s_mov_b32 s1, s71
	s_xor_b64 s[0:1], s[0:1], s[62:63]
	s_add_u32 s34, s0, 0x4a3e000
	s_addc_u32 s35, s1, 0
	s_mul_i32 s8, s37, 0x1e000
	s_add_i32 s8, s8, s23
	s_add_i32 s8, s8, 0x4a00000
	s_add_u32 s30, s0, s8
	s_addc_u32 s31, s1, 0
	s_add_u32 s28, s30, 0x4000
	s_addc_u32 s29, s31, 0
	s_add_u32 s30, s30, 0x3000
	s_addc_u32 s31, s31, 0
	s_waitcnt vmcnt(0) lgkmcnt(0)
	v_pk_add_f32 v[126:127], v[126:127], v[150:151] op_sel_hi:[1,0] neg_lo:[0,1] neg_hi:[0,1]
	v_pk_mul_f32 v[126:127], v[126:127], v[150:151] op_sel:[0,1] op_sel_hi:[1,1]
	v_pk_fma_f32 v[126:127], v[126:127], v[174:175], v[190:191]
	v_pk_add_f32 v[128:129], v[128:129], v[150:151] op_sel_hi:[1,0] neg_lo:[0,1] neg_hi:[0,1]
	v_pk_mul_f32 v[128:129], v[128:129], v[150:151] op_sel:[0,1] op_sel_hi:[1,1]
	v_pk_fma_f32 v[128:129], v[128:129], v[176:177], v[192:193]
	v_pk_add_f32 v[122:123], v[122:123], v[150:151] op_sel_hi:[1,0] neg_lo:[0,1] neg_hi:[0,1]
	v_pk_mul_f32 v[122:123], v[122:123], v[150:151] op_sel:[0,1] op_sel_hi:[1,1]
	v_pk_fma_f32 v[122:123], v[122:123], v[178:179], v[194:195]
	v_pk_add_f32 v[124:125], v[124:125], v[150:151] op_sel_hi:[1,0] neg_lo:[0,1] neg_hi:[0,1]
	v_pk_mul_f32 v[124:125], v[124:125], v[150:151] op_sel:[0,1] op_sel_hi:[1,1]
	v_pk_fma_f32 v[124:125], v[124:125], v[180:181], v[196:197]
	v_pk_add_f32 v[118:119], v[118:119], v[150:151] op_sel_hi:[1,0] neg_lo:[0,1] neg_hi:[0,1]
	v_pk_mul_f32 v[118:119], v[118:119], v[150:151] op_sel:[0,1] op_sel_hi:[1,1]
	v_pk_fma_f32 v[118:119], v[118:119], v[182:183], v[202:203]
	v_pk_add_f32 v[120:121], v[120:121], v[150:151] op_sel_hi:[1,0] neg_lo:[0,1] neg_hi:[0,1]
	v_pk_mul_f32 v[120:121], v[120:121], v[150:151] op_sel:[0,1] op_sel_hi:[1,1]
	v_pk_fma_f32 v[120:121], v[120:121], v[184:185], v[204:205]
	v_pk_add_f32 v[114:115], v[114:115], v[150:151] op_sel_hi:[1,0] neg_lo:[0,1] neg_hi:[0,1]
	v_pk_mul_f32 v[114:115], v[114:115], v[150:151] op_sel:[0,1] op_sel_hi:[1,1]
	v_pk_fma_f32 v[114:115], v[114:115], v[186:187], v[206:207]
	v_pk_add_f32 v[116:117], v[116:117], v[150:151] op_sel_hi:[1,0] neg_lo:[0,1] neg_hi:[0,1]
	v_pk_mul_f32 v[116:117], v[116:117], v[150:151] op_sel:[0,1] op_sel_hi:[1,1]
	v_pk_fma_f32 v[116:117], v[116:117], v[188:189], v[208:209]
	global_store_dwordx4 v144, v[126:129], s[38:39]
	global_store_dwordx4 v144, v[122:125], s[38:39] offset:16
	global_store_dwordx4 v144, v[118:121], s[38:39] offset:512
	global_store_dwordx4 v144, v[114:117], s[38:39] offset:528
	v_pk_add_f32 v[110:111], v[110:111], v[152:153] op_sel_hi:[1,0] neg_lo:[0,1] neg_hi:[0,1]
	v_pk_mul_f32 v[110:111], v[110:111], v[152:153] op_sel:[0,1] op_sel_hi:[1,1]
	v_pk_fma_f32 v[110:111], v[110:111], v[174:175], v[190:191]
	v_pk_add_f32 v[112:113], v[112:113], v[152:153] op_sel_hi:[1,0] neg_lo:[0,1] neg_hi:[0,1]
	v_pk_mul_f32 v[112:113], v[112:113], v[152:153] op_sel:[0,1] op_sel_hi:[1,1]
	v_pk_fma_f32 v[112:113], v[112:113], v[176:177], v[192:193]
	v_pk_add_f32 v[106:107], v[106:107], v[152:153] op_sel_hi:[1,0] neg_lo:[0,1] neg_hi:[0,1]
	v_pk_mul_f32 v[106:107], v[106:107], v[152:153] op_sel:[0,1] op_sel_hi:[1,1]
	v_pk_fma_f32 v[106:107], v[106:107], v[178:179], v[194:195]
	v_pk_add_f32 v[108:109], v[108:109], v[152:153] op_sel_hi:[1,0] neg_lo:[0,1] neg_hi:[0,1]
	v_pk_mul_f32 v[108:109], v[108:109], v[152:153] op_sel:[0,1] op_sel_hi:[1,1]
	v_pk_fma_f32 v[108:109], v[108:109], v[180:181], v[196:197]
	v_pk_add_f32 v[102:103], v[102:103], v[152:153] op_sel_hi:[1,0] neg_lo:[0,1] neg_hi:[0,1]
	v_pk_mul_f32 v[102:103], v[102:103], v[152:153] op_sel:[0,1] op_sel_hi:[1,1]
	v_pk_fma_f32 v[102:103], v[102:103], v[182:183], v[202:203]
	v_pk_add_f32 v[104:105], v[104:105], v[152:153] op_sel_hi:[1,0] neg_lo:[0,1] neg_hi:[0,1]
	v_pk_mul_f32 v[104:105], v[104:105], v[152:153] op_sel:[0,1] op_sel_hi:[1,1]
	v_pk_fma_f32 v[104:105], v[104:105], v[184:185], v[204:205]
	v_pk_add_f32 v[98:99], v[98:99], v[152:153] op_sel_hi:[1,0] neg_lo:[0,1] neg_hi:[0,1]
	v_pk_mul_f32 v[98:99], v[98:99], v[152:153] op_sel:[0,1] op_sel_hi:[1,1]
	v_pk_fma_f32 v[98:99], v[98:99], v[186:187], v[206:207]
	v_pk_add_f32 v[100:101], v[100:101], v[152:153] op_sel_hi:[1,0] neg_lo:[0,1] neg_hi:[0,1]
	v_pk_mul_f32 v[100:101], v[100:101], v[152:153] op_sel:[0,1] op_sel_hi:[1,1]
	v_pk_fma_f32 v[100:101], v[100:101], v[188:189], v[208:209]
	v_add_u32_e32 v210, 0x10000, v144
	global_store_dwordx4 v210, v[110:113], s[38:39]
	global_store_dwordx4 v210, v[106:109], s[38:39] offset:16
	global_store_dwordx4 v210, v[102:105], s[38:39] offset:512
	global_store_dwordx4 v210, v[98:101], s[38:39] offset:528
	v_pk_add_f32 v[94:95], v[94:95], v[154:155] op_sel_hi:[1,0] neg_lo:[0,1] neg_hi:[0,1]
	v_pk_mul_f32 v[94:95], v[94:95], v[154:155] op_sel:[0,1] op_sel_hi:[1,1]
	v_pk_fma_f32 v[94:95], v[94:95], v[174:175], v[190:191]
	v_pk_add_f32 v[96:97], v[96:97], v[154:155] op_sel_hi:[1,0] neg_lo:[0,1] neg_hi:[0,1]
	v_pk_mul_f32 v[96:97], v[96:97], v[154:155] op_sel:[0,1] op_sel_hi:[1,1]
	v_pk_fma_f32 v[96:97], v[96:97], v[176:177], v[192:193]
	v_pk_add_f32 v[90:91], v[90:91], v[154:155] op_sel_hi:[1,0] neg_lo:[0,1] neg_hi:[0,1]
	v_pk_mul_f32 v[90:91], v[90:91], v[154:155] op_sel:[0,1] op_sel_hi:[1,1]
	v_pk_fma_f32 v[90:91], v[90:91], v[178:179], v[194:195]
	v_pk_add_f32 v[92:93], v[92:93], v[154:155] op_sel_hi:[1,0] neg_lo:[0,1] neg_hi:[0,1]
	v_pk_mul_f32 v[92:93], v[92:93], v[154:155] op_sel:[0,1] op_sel_hi:[1,1]
	v_pk_fma_f32 v[92:93], v[92:93], v[180:181], v[196:197]
	v_pk_add_f32 v[86:87], v[86:87], v[154:155] op_sel_hi:[1,0] neg_lo:[0,1] neg_hi:[0,1]
	v_pk_mul_f32 v[86:87], v[86:87], v[154:155] op_sel:[0,1] op_sel_hi:[1,1]
	v_pk_fma_f32 v[86:87], v[86:87], v[182:183], v[202:203]
	v_pk_add_f32 v[88:89], v[88:89], v[154:155] op_sel_hi:[1,0] neg_lo:[0,1] neg_hi:[0,1]
	v_pk_mul_f32 v[88:89], v[88:89], v[154:155] op_sel:[0,1] op_sel_hi:[1,1]
	v_pk_fma_f32 v[88:89], v[88:89], v[184:185], v[204:205]
	v_pk_add_f32 v[82:83], v[82:83], v[154:155] op_sel_hi:[1,0] neg_lo:[0,1] neg_hi:[0,1]
	v_pk_mul_f32 v[82:83], v[82:83], v[154:155] op_sel:[0,1] op_sel_hi:[1,1]
	v_pk_fma_f32 v[82:83], v[82:83], v[186:187], v[206:207]
	v_pk_add_f32 v[84:85], v[84:85], v[154:155] op_sel_hi:[1,0] neg_lo:[0,1] neg_hi:[0,1]
	v_pk_mul_f32 v[84:85], v[84:85], v[154:155] op_sel:[0,1] op_sel_hi:[1,1]
	v_pk_fma_f32 v[84:85], v[84:85], v[188:189], v[208:209]
	v_add_u32_e32 v210, 0x20000, v144
	global_store_dwordx4 v210, v[94:97], s[38:39]
	global_store_dwordx4 v210, v[90:93], s[38:39] offset:16
	global_store_dwordx4 v210, v[86:89], s[38:39] offset:512
	global_store_dwordx4 v210, v[82:85], s[38:39] offset:528
	v_pk_add_f32 v[78:79], v[78:79], v[156:157] op_sel_hi:[1,0] neg_lo:[0,1] neg_hi:[0,1]
	v_pk_mul_f32 v[78:79], v[78:79], v[156:157] op_sel:[0,1] op_sel_hi:[1,1]
	v_pk_fma_f32 v[78:79], v[78:79], v[174:175], v[190:191]
	v_pk_add_f32 v[80:81], v[80:81], v[156:157] op_sel_hi:[1,0] neg_lo:[0,1] neg_hi:[0,1]
	v_pk_mul_f32 v[80:81], v[80:81], v[156:157] op_sel:[0,1] op_sel_hi:[1,1]
	v_pk_fma_f32 v[80:81], v[80:81], v[176:177], v[192:193]
	v_pk_add_f32 v[74:75], v[74:75], v[156:157] op_sel_hi:[1,0] neg_lo:[0,1] neg_hi:[0,1]
	v_pk_mul_f32 v[74:75], v[74:75], v[156:157] op_sel:[0,1] op_sel_hi:[1,1]
	v_pk_fma_f32 v[74:75], v[74:75], v[178:179], v[194:195]
	v_pk_add_f32 v[76:77], v[76:77], v[156:157] op_sel_hi:[1,0] neg_lo:[0,1] neg_hi:[0,1]
	v_pk_mul_f32 v[76:77], v[76:77], v[156:157] op_sel:[0,1] op_sel_hi:[1,1]
	v_pk_fma_f32 v[76:77], v[76:77], v[180:181], v[196:197]
	v_pk_add_f32 v[70:71], v[70:71], v[156:157] op_sel_hi:[1,0] neg_lo:[0,1] neg_hi:[0,1]
	v_pk_mul_f32 v[70:71], v[70:71], v[156:157] op_sel:[0,1] op_sel_hi:[1,1]
	v_pk_fma_f32 v[70:71], v[70:71], v[182:183], v[202:203]
	v_pk_add_f32 v[72:73], v[72:73], v[156:157] op_sel_hi:[1,0] neg_lo:[0,1] neg_hi:[0,1]
	v_pk_mul_f32 v[72:73], v[72:73], v[156:157] op_sel:[0,1] op_sel_hi:[1,1]
	v_pk_fma_f32 v[72:73], v[72:73], v[184:185], v[204:205]
	v_pk_add_f32 v[66:67], v[66:67], v[156:157] op_sel_hi:[1,0] neg_lo:[0,1] neg_hi:[0,1]
	v_pk_mul_f32 v[66:67], v[66:67], v[156:157] op_sel:[0,1] op_sel_hi:[1,1]
	v_pk_fma_f32 v[66:67], v[66:67], v[186:187], v[206:207]
	v_pk_add_f32 v[68:69], v[68:69], v[156:157] op_sel_hi:[1,0] neg_lo:[0,1] neg_hi:[0,1]
	v_pk_mul_f32 v[68:69], v[68:69], v[156:157] op_sel:[0,1] op_sel_hi:[1,1]
	v_pk_fma_f32 v[68:69], v[68:69], v[188:189], v[208:209]
	v_add_u32_e32 v210, 0x30000, v144
	global_store_dwordx4 v210, v[78:81], s[38:39]
	global_store_dwordx4 v210, v[74:77], s[38:39] offset:16
	global_store_dwordx4 v210, v[70:73], s[38:39] offset:512
	global_store_dwordx4 v210, v[66:69], s[38:39] offset:528
	v_pk_add_f32 v[62:63], v[62:63], v[158:159] op_sel_hi:[1,0] neg_lo:[0,1] neg_hi:[0,1]
	v_pk_mul_f32 v[62:63], v[62:63], v[158:159] op_sel:[0,1] op_sel_hi:[1,1]
	v_pk_fma_f32 v[62:63], v[62:63], v[174:175], v[190:191]
	v_pk_add_f32 v[64:65], v[64:65], v[158:159] op_sel_hi:[1,0] neg_lo:[0,1] neg_hi:[0,1]
	v_pk_mul_f32 v[64:65], v[64:65], v[158:159] op_sel:[0,1] op_sel_hi:[1,1]
	v_pk_fma_f32 v[64:65], v[64:65], v[176:177], v[192:193]
	v_pk_add_f32 v[58:59], v[58:59], v[158:159] op_sel_hi:[1,0] neg_lo:[0,1] neg_hi:[0,1]
	v_pk_mul_f32 v[58:59], v[58:59], v[158:159] op_sel:[0,1] op_sel_hi:[1,1]
	v_pk_fma_f32 v[58:59], v[58:59], v[178:179], v[194:195]
	v_pk_add_f32 v[60:61], v[60:61], v[158:159] op_sel_hi:[1,0] neg_lo:[0,1] neg_hi:[0,1]
	v_pk_mul_f32 v[60:61], v[60:61], v[158:159] op_sel:[0,1] op_sel_hi:[1,1]
	v_pk_fma_f32 v[60:61], v[60:61], v[180:181], v[196:197]
	v_pk_add_f32 v[54:55], v[54:55], v[158:159] op_sel_hi:[1,0] neg_lo:[0,1] neg_hi:[0,1]
	v_pk_mul_f32 v[54:55], v[54:55], v[158:159] op_sel:[0,1] op_sel_hi:[1,1]
	v_pk_fma_f32 v[54:55], v[54:55], v[182:183], v[202:203]
	v_pk_add_f32 v[56:57], v[56:57], v[158:159] op_sel_hi:[1,0] neg_lo:[0,1] neg_hi:[0,1]
	v_pk_mul_f32 v[56:57], v[56:57], v[158:159] op_sel:[0,1] op_sel_hi:[1,1]
	v_pk_fma_f32 v[56:57], v[56:57], v[184:185], v[204:205]
	v_pk_add_f32 v[50:51], v[50:51], v[158:159] op_sel_hi:[1,0] neg_lo:[0,1] neg_hi:[0,1]
	v_pk_mul_f32 v[50:51], v[50:51], v[158:159] op_sel:[0,1] op_sel_hi:[1,1]
	v_pk_fma_f32 v[50:51], v[50:51], v[186:187], v[206:207]
	v_pk_add_f32 v[52:53], v[52:53], v[158:159] op_sel_hi:[1,0] neg_lo:[0,1] neg_hi:[0,1]
	v_pk_mul_f32 v[52:53], v[52:53], v[158:159] op_sel:[0,1] op_sel_hi:[1,1]
	v_pk_fma_f32 v[52:53], v[52:53], v[188:189], v[208:209]
	v_add_u32_e32 v210, 0x80000, v144
	global_store_dwordx4 v210, v[62:65], s[38:39]
	global_store_dwordx4 v210, v[58:61], s[38:39] offset:16
	global_store_dwordx4 v210, v[54:57], s[38:39] offset:512
	global_store_dwordx4 v210, v[50:53], s[38:39] offset:528
	v_pk_add_f32 v[46:47], v[46:47], v[160:161] op_sel_hi:[1,0] neg_lo:[0,1] neg_hi:[0,1]
	v_pk_mul_f32 v[46:47], v[46:47], v[160:161] op_sel:[0,1] op_sel_hi:[1,1]
	v_pk_fma_f32 v[46:47], v[46:47], v[174:175], v[190:191]
	v_pk_add_f32 v[48:49], v[48:49], v[160:161] op_sel_hi:[1,0] neg_lo:[0,1] neg_hi:[0,1]
	v_pk_mul_f32 v[48:49], v[48:49], v[160:161] op_sel:[0,1] op_sel_hi:[1,1]
	v_pk_fma_f32 v[48:49], v[48:49], v[176:177], v[192:193]
	v_pk_add_f32 v[42:43], v[42:43], v[160:161] op_sel_hi:[1,0] neg_lo:[0,1] neg_hi:[0,1]
	v_pk_mul_f32 v[42:43], v[42:43], v[160:161] op_sel:[0,1] op_sel_hi:[1,1]
	v_pk_fma_f32 v[42:43], v[42:43], v[178:179], v[194:195]
	v_pk_add_f32 v[44:45], v[44:45], v[160:161] op_sel_hi:[1,0] neg_lo:[0,1] neg_hi:[0,1]
	v_pk_mul_f32 v[44:45], v[44:45], v[160:161] op_sel:[0,1] op_sel_hi:[1,1]
	v_pk_fma_f32 v[44:45], v[44:45], v[180:181], v[196:197]
	v_pk_add_f32 v[38:39], v[38:39], v[160:161] op_sel_hi:[1,0] neg_lo:[0,1] neg_hi:[0,1]
	v_pk_mul_f32 v[38:39], v[38:39], v[160:161] op_sel:[0,1] op_sel_hi:[1,1]
	v_pk_fma_f32 v[38:39], v[38:39], v[182:183], v[202:203]
	v_pk_add_f32 v[40:41], v[40:41], v[160:161] op_sel_hi:[1,0] neg_lo:[0,1] neg_hi:[0,1]
	v_pk_mul_f32 v[40:41], v[40:41], v[160:161] op_sel:[0,1] op_sel_hi:[1,1]
	v_pk_fma_f32 v[40:41], v[40:41], v[184:185], v[204:205]
	v_pk_add_f32 v[34:35], v[34:35], v[160:161] op_sel_hi:[1,0] neg_lo:[0,1] neg_hi:[0,1]
	v_pk_mul_f32 v[34:35], v[34:35], v[160:161] op_sel:[0,1] op_sel_hi:[1,1]
	v_pk_fma_f32 v[34:35], v[34:35], v[186:187], v[206:207]
	v_pk_add_f32 v[36:37], v[36:37], v[160:161] op_sel_hi:[1,0] neg_lo:[0,1] neg_hi:[0,1]
	v_pk_mul_f32 v[36:37], v[36:37], v[160:161] op_sel:[0,1] op_sel_hi:[1,1]
	v_pk_fma_f32 v[36:37], v[36:37], v[188:189], v[208:209]
	v_add_u32_e32 v210, 0x90000, v144
	global_store_dwordx4 v210, v[46:49], s[38:39]
	global_store_dwordx4 v210, v[42:45], s[38:39] offset:16
	global_store_dwordx4 v210, v[38:41], s[38:39] offset:512
	global_store_dwordx4 v210, v[34:37], s[38:39] offset:528
	v_pk_add_f32 v[30:31], v[30:31], v[162:163] op_sel_hi:[1,0] neg_lo:[0,1] neg_hi:[0,1]
	v_pk_mul_f32 v[30:31], v[30:31], v[162:163] op_sel:[0,1] op_sel_hi:[1,1]
	v_pk_fma_f32 v[30:31], v[30:31], v[174:175], v[190:191]
	v_pk_add_f32 v[32:33], v[32:33], v[162:163] op_sel_hi:[1,0] neg_lo:[0,1] neg_hi:[0,1]
	v_pk_mul_f32 v[32:33], v[32:33], v[162:163] op_sel:[0,1] op_sel_hi:[1,1]
	v_pk_fma_f32 v[32:33], v[32:33], v[176:177], v[192:193]
	v_pk_add_f32 v[26:27], v[26:27], v[162:163] op_sel_hi:[1,0] neg_lo:[0,1] neg_hi:[0,1]
	v_pk_mul_f32 v[26:27], v[26:27], v[162:163] op_sel:[0,1] op_sel_hi:[1,1]
	v_pk_fma_f32 v[26:27], v[26:27], v[178:179], v[194:195]
	v_pk_add_f32 v[28:29], v[28:29], v[162:163] op_sel_hi:[1,0] neg_lo:[0,1] neg_hi:[0,1]
	v_pk_mul_f32 v[28:29], v[28:29], v[162:163] op_sel:[0,1] op_sel_hi:[1,1]
	v_pk_fma_f32 v[28:29], v[28:29], v[180:181], v[196:197]
	v_pk_add_f32 v[22:23], v[22:23], v[162:163] op_sel_hi:[1,0] neg_lo:[0,1] neg_hi:[0,1]
	v_pk_mul_f32 v[22:23], v[22:23], v[162:163] op_sel:[0,1] op_sel_hi:[1,1]
	v_pk_fma_f32 v[22:23], v[22:23], v[182:183], v[202:203]
	v_pk_add_f32 v[24:25], v[24:25], v[162:163] op_sel_hi:[1,0] neg_lo:[0,1] neg_hi:[0,1]
	v_pk_mul_f32 v[24:25], v[24:25], v[162:163] op_sel:[0,1] op_sel_hi:[1,1]
	v_pk_fma_f32 v[24:25], v[24:25], v[184:185], v[204:205]
	v_pk_add_f32 v[18:19], v[18:19], v[162:163] op_sel_hi:[1,0] neg_lo:[0,1] neg_hi:[0,1]
	v_pk_mul_f32 v[18:19], v[18:19], v[162:163] op_sel:[0,1] op_sel_hi:[1,1]
	v_pk_fma_f32 v[18:19], v[18:19], v[186:187], v[206:207]
	v_pk_add_f32 v[20:21], v[20:21], v[162:163] op_sel_hi:[1,0] neg_lo:[0,1] neg_hi:[0,1]
	v_pk_mul_f32 v[20:21], v[20:21], v[162:163] op_sel:[0,1] op_sel_hi:[1,1]
	v_pk_fma_f32 v[20:21], v[20:21], v[188:189], v[208:209]
	v_add_u32_e32 v210, 0xa0000, v144
	global_store_dwordx4 v210, v[30:33], s[38:39]
	global_store_dwordx4 v210, v[26:29], s[38:39] offset:16
	global_store_dwordx4 v210, v[22:25], s[38:39] offset:512
	global_store_dwordx4 v210, v[18:21], s[38:39] offset:528
	v_pk_add_f32 v[14:15], v[14:15], v[164:165] op_sel_hi:[1,0] neg_lo:[0,1] neg_hi:[0,1]
	v_pk_mul_f32 v[14:15], v[14:15], v[164:165] op_sel:[0,1] op_sel_hi:[1,1]
	v_pk_fma_f32 v[14:15], v[14:15], v[174:175], v[190:191]
	v_pk_add_f32 v[16:17], v[16:17], v[164:165] op_sel_hi:[1,0] neg_lo:[0,1] neg_hi:[0,1]
	v_pk_mul_f32 v[16:17], v[16:17], v[164:165] op_sel:[0,1] op_sel_hi:[1,1]
	v_pk_fma_f32 v[16:17], v[16:17], v[176:177], v[192:193]
	v_pk_add_f32 v[10:11], v[10:11], v[164:165] op_sel_hi:[1,0] neg_lo:[0,1] neg_hi:[0,1]
	v_pk_mul_f32 v[10:11], v[10:11], v[164:165] op_sel:[0,1] op_sel_hi:[1,1]
	v_pk_fma_f32 v[10:11], v[10:11], v[178:179], v[194:195]
	v_pk_add_f32 v[12:13], v[12:13], v[164:165] op_sel_hi:[1,0] neg_lo:[0,1] neg_hi:[0,1]
	v_pk_mul_f32 v[12:13], v[12:13], v[164:165] op_sel:[0,1] op_sel_hi:[1,1]
	v_pk_fma_f32 v[12:13], v[12:13], v[180:181], v[196:197]
	v_pk_add_f32 v[6:7], v[6:7], v[164:165] op_sel_hi:[1,0] neg_lo:[0,1] neg_hi:[0,1]
	v_pk_mul_f32 v[6:7], v[6:7], v[164:165] op_sel:[0,1] op_sel_hi:[1,1]
	v_pk_fma_f32 v[6:7], v[6:7], v[182:183], v[202:203]
	v_pk_add_f32 v[8:9], v[8:9], v[164:165] op_sel_hi:[1,0] neg_lo:[0,1] neg_hi:[0,1]
	v_pk_mul_f32 v[8:9], v[8:9], v[164:165] op_sel:[0,1] op_sel_hi:[1,1]
	v_pk_fma_f32 v[8:9], v[8:9], v[184:185], v[204:205]
	v_pk_add_f32 v[2:3], v[2:3], v[164:165] op_sel_hi:[1,0] neg_lo:[0,1] neg_hi:[0,1]
	v_pk_mul_f32 v[2:3], v[2:3], v[164:165] op_sel:[0,1] op_sel_hi:[1,1]
	v_pk_fma_f32 v[2:3], v[2:3], v[186:187], v[206:207]
	v_pk_add_f32 v[4:5], v[4:5], v[164:165] op_sel_hi:[1,0] neg_lo:[0,1] neg_hi:[0,1]
	v_pk_mul_f32 v[4:5], v[4:5], v[164:165] op_sel:[0,1] op_sel_hi:[1,1]
	v_pk_fma_f32 v[4:5], v[4:5], v[188:189], v[208:209]
	v_add_u32_e32 v210, 0xb0000, v144
	global_store_dwordx4 v210, v[14:17], s[38:39]
	global_store_dwordx4 v210, v[10:13], s[38:39] offset:16
	global_store_dwordx4 v210, v[6:9], s[38:39] offset:512
	global_store_dwordx4 v210, v[2:5], s[38:39] offset:528
	global_load_dwordx4 v[174:177], v146, s[28:29]
	global_load_dwordx4 v[178:181], v146, s[28:29] offset:16
	global_load_dwordx4 v[182:185], v146, s[28:29] offset:512
	global_load_dwordx4 v[186:189], v146, s[28:29] offset:528
	global_load_dwordx4 v[190:193], v146, s[30:31]
	global_load_dwordx4 v[194:197], v146, s[30:31] offset:16
	global_load_dwordx4 v[202:205], v146, s[30:31] offset:512
	global_load_dwordx4 v[206:209], v146, s[30:31] offset:528
	s_waitcnt vmcnt(0)
	v_pk_add_f32 v[174:175], v[174:175], 1.0 op_sel_hi:[1,0]
	v_pk_add_f32 v[176:177], v[176:177], 1.0 op_sel_hi:[1,0]
	v_pk_add_f32 v[178:179], v[178:179], 1.0 op_sel_hi:[1,0]
	v_pk_add_f32 v[180:181], v[180:181], 1.0 op_sel_hi:[1,0]
	v_pk_add_f32 v[182:183], v[182:183], 1.0 op_sel_hi:[1,0]
	v_pk_add_f32 v[184:185], v[184:185], 1.0 op_sel_hi:[1,0]
	v_pk_add_f32 v[186:187], v[186:187], 1.0 op_sel_hi:[1,0]
	v_pk_add_f32 v[188:189], v[188:189], 1.0 op_sel_hi:[1,0]
	v_pk_fma_f32 v[220:221], v[126:127], v[174:175], v[190:191]
	v_pk_fma_f32 v[222:223], v[128:129], v[176:177], v[192:193]
	v_cvt_pk_bf16_f32 v212, v220, v221
	v_cvt_pk_bf16_f32 v213, v222, v223
	v_pk_fma_f32 v[220:221], v[122:123], v[178:179], v[194:195]
	v_pk_fma_f32 v[222:223], v[124:125], v[180:181], v[196:197]
	v_cvt_pk_bf16_f32 v214, v220, v221
	v_cvt_pk_bf16_f32 v215, v222, v223
	global_store_dwordx4 v145, v[212:215], s[34:35]
	v_pk_fma_f32 v[220:221], v[118:119], v[182:183], v[202:203]
	v_pk_fma_f32 v[222:223], v[120:121], v[184:185], v[204:205]
	v_cvt_pk_bf16_f32 v216, v220, v221
	v_cvt_pk_bf16_f32 v217, v222, v223
	v_pk_fma_f32 v[220:221], v[114:115], v[186:187], v[206:207]
	v_pk_fma_f32 v[222:223], v[116:117], v[188:189], v[208:209]
	v_cvt_pk_bf16_f32 v218, v220, v221
	v_cvt_pk_bf16_f32 v219, v222, v223
	global_store_dwordx4 v145, v[216:219], s[34:35] offset:256
	v_add_u32_e32 v211, 0x8000, v145
	v_pk_fma_f32 v[220:221], v[110:111], v[174:175], v[190:191]
	v_pk_fma_f32 v[222:223], v[112:113], v[176:177], v[192:193]
	v_cvt_pk_bf16_f32 v212, v220, v221
	v_cvt_pk_bf16_f32 v213, v222, v223
	v_pk_fma_f32 v[220:221], v[106:107], v[178:179], v[194:195]
	v_pk_fma_f32 v[222:223], v[108:109], v[180:181], v[196:197]
	v_cvt_pk_bf16_f32 v214, v220, v221
	v_cvt_pk_bf16_f32 v215, v222, v223
	global_store_dwordx4 v211, v[212:215], s[34:35]
	v_pk_fma_f32 v[220:221], v[102:103], v[182:183], v[202:203]
	v_pk_fma_f32 v[222:223], v[104:105], v[184:185], v[204:205]
	v_cvt_pk_bf16_f32 v216, v220, v221
	v_cvt_pk_bf16_f32 v217, v222, v223
	v_pk_fma_f32 v[220:221], v[98:99], v[186:187], v[206:207]
	v_pk_fma_f32 v[222:223], v[100:101], v[188:189], v[208:209]
	v_cvt_pk_bf16_f32 v218, v220, v221
	v_cvt_pk_bf16_f32 v219, v222, v223
	global_store_dwordx4 v211, v[216:219], s[34:35] offset:256
	v_add_u32_e32 v211, 0x10000, v145
	v_pk_fma_f32 v[220:221], v[94:95], v[174:175], v[190:191]
	v_pk_fma_f32 v[222:223], v[96:97], v[176:177], v[192:193]
	v_cvt_pk_bf16_f32 v212, v220, v221
	v_cvt_pk_bf16_f32 v213, v222, v223
	v_pk_fma_f32 v[220:221], v[90:91], v[178:179], v[194:195]
	v_pk_fma_f32 v[222:223], v[92:93], v[180:181], v[196:197]
	v_cvt_pk_bf16_f32 v214, v220, v221
	v_cvt_pk_bf16_f32 v215, v222, v223
	global_store_dwordx4 v211, v[212:215], s[34:35]
	v_pk_fma_f32 v[220:221], v[86:87], v[182:183], v[202:203]
	v_pk_fma_f32 v[222:223], v[88:89], v[184:185], v[204:205]
	v_cvt_pk_bf16_f32 v216, v220, v221
	v_cvt_pk_bf16_f32 v217, v222, v223
	v_pk_fma_f32 v[220:221], v[82:83], v[186:187], v[206:207]
	v_pk_fma_f32 v[222:223], v[84:85], v[188:189], v[208:209]
	v_cvt_pk_bf16_f32 v218, v220, v221
	v_cvt_pk_bf16_f32 v219, v222, v223
	global_store_dwordx4 v211, v[216:219], s[34:35] offset:256
	v_add_u32_e32 v211, 0x18000, v145
	v_pk_fma_f32 v[220:221], v[78:79], v[174:175], v[190:191]
	v_pk_fma_f32 v[222:223], v[80:81], v[176:177], v[192:193]
	v_cvt_pk_bf16_f32 v212, v220, v221
	v_cvt_pk_bf16_f32 v213, v222, v223
	v_pk_fma_f32 v[220:221], v[74:75], v[178:179], v[194:195]
	v_pk_fma_f32 v[222:223], v[76:77], v[180:181], v[196:197]
	v_cvt_pk_bf16_f32 v214, v220, v221
	v_cvt_pk_bf16_f32 v215, v222, v223
	global_store_dwordx4 v211, v[212:215], s[34:35]
	v_pk_fma_f32 v[220:221], v[70:71], v[182:183], v[202:203]
	v_pk_fma_f32 v[222:223], v[72:73], v[184:185], v[204:205]
	v_cvt_pk_bf16_f32 v216, v220, v221
	v_cvt_pk_bf16_f32 v217, v222, v223
	v_pk_fma_f32 v[220:221], v[66:67], v[186:187], v[206:207]
	v_pk_fma_f32 v[222:223], v[68:69], v[188:189], v[208:209]
	v_cvt_pk_bf16_f32 v218, v220, v221
	v_cvt_pk_bf16_f32 v219, v222, v223
	global_store_dwordx4 v211, v[216:219], s[34:35] offset:256
	v_add_u32_e32 v211, 0x40000, v145
	v_pk_fma_f32 v[220:221], v[62:63], v[174:175], v[190:191]
	v_pk_fma_f32 v[222:223], v[64:65], v[176:177], v[192:193]
	v_cvt_pk_bf16_f32 v212, v220, v221
	v_cvt_pk_bf16_f32 v213, v222, v223
	v_pk_fma_f32 v[220:221], v[58:59], v[178:179], v[194:195]
	v_pk_fma_f32 v[222:223], v[60:61], v[180:181], v[196:197]
	v_cvt_pk_bf16_f32 v214, v220, v221
	v_cvt_pk_bf16_f32 v215, v222, v223
	global_store_dwordx4 v211, v[212:215], s[34:35]
	v_pk_fma_f32 v[220:221], v[54:55], v[182:183], v[202:203]
	v_pk_fma_f32 v[222:223], v[56:57], v[184:185], v[204:205]
	v_cvt_pk_bf16_f32 v216, v220, v221
	v_cvt_pk_bf16_f32 v217, v222, v223
	v_pk_fma_f32 v[220:221], v[50:51], v[186:187], v[206:207]
	v_pk_fma_f32 v[222:223], v[52:53], v[188:189], v[208:209]
	v_cvt_pk_bf16_f32 v218, v220, v221
	v_cvt_pk_bf16_f32 v219, v222, v223
	global_store_dwordx4 v211, v[216:219], s[34:35] offset:256
	v_add_u32_e32 v211, 0x48000, v145
	v_pk_fma_f32 v[220:221], v[46:47], v[174:175], v[190:191]
	v_pk_fma_f32 v[222:223], v[48:49], v[176:177], v[192:193]
	v_cvt_pk_bf16_f32 v212, v220, v221
	v_cvt_pk_bf16_f32 v213, v222, v223
	v_pk_fma_f32 v[220:221], v[42:43], v[178:179], v[194:195]
	v_pk_fma_f32 v[222:223], v[44:45], v[180:181], v[196:197]
	v_cvt_pk_bf16_f32 v214, v220, v221
	v_cvt_pk_bf16_f32 v215, v222, v223
	global_store_dwordx4 v211, v[212:215], s[34:35]
	v_pk_fma_f32 v[220:221], v[38:39], v[182:183], v[202:203]
	v_pk_fma_f32 v[222:223], v[40:41], v[184:185], v[204:205]
	v_cvt_pk_bf16_f32 v216, v220, v221
	v_cvt_pk_bf16_f32 v217, v222, v223
	v_pk_fma_f32 v[220:221], v[34:35], v[186:187], v[206:207]
	v_pk_fma_f32 v[222:223], v[36:37], v[188:189], v[208:209]
	v_cvt_pk_bf16_f32 v218, v220, v221
	v_cvt_pk_bf16_f32 v219, v222, v223
	global_store_dwordx4 v211, v[216:219], s[34:35] offset:256
	v_add_u32_e32 v211, 0x50000, v145
	v_pk_fma_f32 v[220:221], v[30:31], v[174:175], v[190:191]
	v_pk_fma_f32 v[222:223], v[32:33], v[176:177], v[192:193]
	v_cvt_pk_bf16_f32 v212, v220, v221
	v_cvt_pk_bf16_f32 v213, v222, v223
	v_pk_fma_f32 v[220:221], v[26:27], v[178:179], v[194:195]
	v_pk_fma_f32 v[222:223], v[28:29], v[180:181], v[196:197]
	v_cvt_pk_bf16_f32 v214, v220, v221
	v_cvt_pk_bf16_f32 v215, v222, v223
	global_store_dwordx4 v211, v[212:215], s[34:35]
	v_pk_fma_f32 v[220:221], v[22:23], v[182:183], v[202:203]
	v_pk_fma_f32 v[222:223], v[24:25], v[184:185], v[204:205]
	v_cvt_pk_bf16_f32 v216, v220, v221
	v_cvt_pk_bf16_f32 v217, v222, v223
	v_pk_fma_f32 v[220:221], v[18:19], v[186:187], v[206:207]
	v_pk_fma_f32 v[222:223], v[20:21], v[188:189], v[208:209]
	v_cvt_pk_bf16_f32 v218, v220, v221
	v_cvt_pk_bf16_f32 v219, v222, v223
	global_store_dwordx4 v211, v[216:219], s[34:35] offset:256
	v_add_u32_e32 v211, 0x58000, v145
	v_pk_fma_f32 v[220:221], v[14:15], v[174:175], v[190:191]
	v_pk_fma_f32 v[222:223], v[16:17], v[176:177], v[192:193]
	v_cvt_pk_bf16_f32 v212, v220, v221
	v_cvt_pk_bf16_f32 v213, v222, v223
	v_pk_fma_f32 v[220:221], v[10:11], v[178:179], v[194:195]
	v_pk_fma_f32 v[222:223], v[12:13], v[180:181], v[196:197]
	v_cvt_pk_bf16_f32 v214, v220, v221
	v_cvt_pk_bf16_f32 v215, v222, v223
	global_store_dwordx4 v211, v[212:215], s[34:35]
	v_pk_fma_f32 v[220:221], v[6:7], v[182:183], v[202:203]
	v_pk_fma_f32 v[222:223], v[8:9], v[184:185], v[204:205]
	v_cvt_pk_bf16_f32 v216, v220, v221
	v_cvt_pk_bf16_f32 v217, v222, v223
	v_pk_fma_f32 v[220:221], v[2:3], v[186:187], v[206:207]
	v_pk_fma_f32 v[222:223], v[4:5], v[188:189], v[208:209]
	v_cvt_pk_bf16_f32 v218, v220, v221
	v_cvt_pk_bf16_f32 v219, v222, v223
	global_store_dwordx4 v211, v[216:219], s[34:35] offset:256
	s_andn2_b64 vcc, exec, s[4:5]
	s_mov_b64 s[0:1], -1
	s_cbranch_vccnz .LBB0_809
	s_andn2_b64 vcc, exec, s[10:11]
	s_cbranch_vccnz .LBB0_808
	s_barrier
	s_branch .LBB0_808

.LBB0_1029:
	s_or_b64 exec, exec, s[0:1]
	s_waitcnt lgkmcnt(0)
	s_barrier
	s_mov_b64 s[6:7], exec
	s_mov_b32 s83, s71
.LBB0_1032:
	v_writelane_b32 v255, s82, 18
	s_nop 1
	v_writelane_b32 v255, s83, 19
	s_mov_b64 s[82:83], 0x20000
	s_or_b64 exec, exec, s[6:7]
	s_mov_b32 s0, s91
	s_mov_b32 s70, 0
	s_waitcnt vmcnt(0)
	s_waitcnt lgkmcnt(0)
	v_or_b32_e32 v0, s0, v230
	v_cmp_eq_u32_e32 vcc, 0, v0
	s_barrier
	s_and_saveexec_b64 s[0:1], vcc
	s_cbranch_execz .LBB0_1076
.LBB0_1076:
	s_or_b64 exec, exec, s[0:1]
	v_readlane_b32 s4, v254, 53
	v_readlane_b32 s5, v254, 54
	s_lshl_b64 s[38:39], s[4:5], 23
	s_mov_b32 s1, s91
	v_readlane_b32 s4, v253, 27
	s_waitcnt lgkmcnt(0)
	s_barrier
	s_mov_b32 s36, 0
	s_mov_b32 s0, 0
	v_readlane_b32 s5, v253, 28
	v_or_b32_e32 v8, s1, v230
	s_mov_b32 s37, s71
	s_andn2_b64 vcc, exec, s[4:5]
	v_readfirstlane_b32 s4, v8
	s_cbranch_vccnz .LBB0_1096
	v_lshlrev_b32_e32 v0, 4, v8
	v_add_u32_e32 v3, 0x2000, v0
	v_ashrrev_i32_e32 v2, 31, v3
	v_lshrrev_b32_e32 v2, 22, v2
	v_add_u32_e32 v2, v3, v2
	v_ashrrev_i32_e32 v2, 10, v2
	v_mul_i32_i24_e32 v4, 0x400, v2
	v_sub_u32_e32 v3, v3, v4
	v_lshrrev_b32_e32 v4, 4, v3
	v_bitop3_b32 v4, v4, v3, 32 bitop3:0x6c
	s_xor_b64 s[6:7], s[36:37], s[62:63]
	v_ashrrev_i32_e32 v3, 31, v4
	s_add_u32 s22, s6, 0x4a3e000
	s_mov_b32 s1, s37
	v_lshrrev_b32_e32 v3, 26, v3
	s_addc_u32 s23, s7, 0
	s_xor_b64 s[0:1], s[0:1], s[62:63]
	v_add_u32_e32 v5, v4, v3
	v_lshlrev_b32_e32 v6, 3, v2
	s_add_u32 s0, s0, s38
	v_ashrrev_i32_e32 v3, 6, v5
	v_and_b32_e32 v6, -16, v6
	s_addc_u32 s1, s1, s39
	v_add_u32_e32 v6, v3, v6
	s_add_u32 s24, s0, 0x2500000
	v_and_b32_e32 v7, 3, v3
	s_mov_b32 s0, 0x1fffe0
	v_lshrrev_b32_e32 v9, 2, v6
	v_lshlrev_b32_e32 v10, 1, v6
	v_and_b32_e32 v5, 0xc0, v5
	v_and_or_b32 v7, v6, s0, v7
	v_and_b32_e32 v9, 4, v9
	v_and_b32_e32 v10, 24, v10
	v_sub_u32_e32 v4, v4, v5
	v_or3_b32 v7, v7, v9, v10
	v_lshlrev_b32_e32 v9, 5, v2
	v_ashrrev_i16_sdwa v4, v237, sext(v4) dst_sel:DWORD dst_unused:UNUSED_PAD src0_sel:DWORD src1_sel:BYTE_0
	v_and_b32_e32 v9, 32, v9
	v_bfe_i32 v4, v4, 0, 16
	v_add_lshl_u32 v5, v9, v4, 1
	v_lshl_add_u32 v130, v7, 11, v5
	v_lshl_add_u32 v132, v6, 11, v5
	v_bfe_i32 v5, v8, 27, 1
	v_lshrrev_b32_e32 v5, 22, v5
	v_add_u32_e32 v5, v0, v5
	v_and_b32_e32 v5, 0xfffffc00, v5
	v_sub_u32_e32 v0, v0, v5
	v_lshrrev_b32_e32 v5, 4, v0
	v_ashrrev_i32_e32 v6, 31, v8
	v_bitop3_b32 v0, v5, v0, 32 bitop3:0x6c
	v_lshrrev_b32_e32 v6, 26, v6
	v_ashrrev_i32_e32 v5, 31, v0
	v_add_u32_e32 v6, v8, v6
	v_lshrrev_b32_e32 v5, 26, v5
	v_ashrrev_i32_e32 v6, 6, v6
	v_add_u32_e32 v7, v0, v5
	v_lshlrev_b32_e32 v9, 3, v6
	v_ashrrev_i32_e32 v5, 6, v7
	v_and_b32_e32 v9, -16, v9
	v_add_u32_e32 v9, v5, v9
	v_and_b32_e32 v10, 3, v5
	v_lshrrev_b32_e32 v11, 2, v9
	v_lshlrev_b32_e32 v12, 1, v9
	v_and_b32_e32 v7, 0xc0, v7
	s_addc_u32 s25, s1, 0
	s_ashr_i32 s5, s4, 6
	v_and_or_b32 v10, v9, s0, v10
	v_and_b32_e32 v11, 4, v11
	v_and_b32_e32 v12, 24, v12
	v_sub_u32_e32 v0, v0, v7
	s_ashr_i32 s6, s4, 8
	s_lshl_b32 s26, s5, 10
	v_or3_b32 v10, v10, v11, v12
	v_lshlrev_b32_e32 v11, 5, v6
	v_ashrrev_i16_sdwa v0, v237, sext(v0) dst_sel:DWORD dst_unused:UNUSED_PAD src0_sel:DWORD src1_sel:BYTE_0
	v_readlane_b32 s0, v253, 34
	v_and_b32_e32 v11, 32, v11
	v_bfe_i32 v7, v0, 0, 16
	v_readlane_b32 s1, v253, 35
	s_add_u32 s16, s24, s0
	v_add_lshl_u32 v11, v11, v7, 1
	s_addc_u32 s17, s25, s1
	s_add_i32 s27, s26, 0
	v_lshl_add_u32 v0, v10, 11, v11
	s_add_i32 m0, s27, 0x10000
	v_lshl_add_u32 v134, v9, 11, v11
	global_load_lds_dwordx4 v0, s[16:17]
	s_add_i32 m0, s27, 0x12000
	s_add_u32 s0, s16, 0x40000
	global_load_lds_dwordx4 v130, s[16:17]
	s_addc_u32 s1, s17, 0
	s_add_i32 m0, s27, 0x14000
	s_mov_b32 s51, s37
	global_load_lds_dwordx4 v0, s[0:1]
	s_add_i32 m0, s27, 0x16000
	s_nop 0
	global_load_lds_dwordx4 v130, s[0:1]
	v_readlane_b32 s0, v253, 58
	v_readlane_b32 s1, v253, 59
	s_add_u32 s18, s22, s0
	s_addc_u32 s19, s23, s1
	s_add_i32 s28, s27, 0x2000
	s_mov_b32 m0, s27
	s_add_u32 s0, s18, 0x40000
	global_load_lds_dwordx4 v134, s[18:19]
	s_mov_b32 m0, s28
	s_addc_u32 s1, s19, 0
	s_add_i32 s29, s27, 0x4000
	global_load_lds_dwordx4 v132, s[18:19]
	s_mov_b32 m0, s29
	s_add_i32 s30, s27, 0x6000
	global_load_lds_dwordx4 v134, s[0:1]
	s_mov_b32 m0, s30
	s_cmp_eq_u32 s6, 1
	global_load_lds_dwordx4 v132, s[0:1]
	s_cselect_b64 s[0:1], -1, 0
	s_cmp_lg_u32 s6, 1
	s_cbranch_scc1 .LBB0_1079
	s_barrier
